# grid barrier: the acquire (buffer_inv sc1) is issued right after the arrival atomic returns, before polling / before the leader's write-back, instead of after the release is observed (no L1-allocating
# speedup vs baseline: 1.0175x; 1.0175x over previous
.LBB0_235:
	s_or_b64 exec, exec, s[6:7]
	v_cvt_f32_u32_e32 v4, v2
	s_waitcnt vmcnt(0)
	buffer_inv sc1
	v_readfirstlane_b32 s4, v3
	v_sub_u32_e32 v3, 0, v2
	v_rcp_iflag_f32_e32 v4, v4
	v_add_u32_e32 v5, s4, v1
	v_mul_f32_e32 v4, 0x4f7ffffe, v4
	v_cvt_u32_f32_e32 v4, v4
	v_mul_lo_u32 v1, v3, v4
	v_mul_hi_u32 v1, v4, v1
	v_add_u32_e32 v1, v4, v1
	v_mul_hi_u32 v1, v5, v1
	v_mul_lo_u32 v3, v1, v2
	v_sub_u32_e32 v3, v5, v3
	v_add_u32_e32 v4, 1, v1
	v_cmp_ge_u32_e32 vcc, v3, v2
	s_nop 1
	v_cndmask_b32_e32 v1, v1, v4, vcc
	v_sub_u32_e32 v4, v3, v2
	v_cndmask_b32_e32 v3, v3, v4, vcc
	v_add_u32_e32 v4, 1, v1
	v_cmp_ge_u32_e32 vcc, v3, v2
	v_add_u32_e32 v3, 1, v5
	s_nop 0
	v_cndmask_b32_e32 v1, v1, v4, vcc
	v_mul_lo_u32 v4, v2, v1
	v_add_u32_e32 v2, v4, v2
	v_cmp_ne_u32_e32 vcc, v3, v2
	s_and_saveexec_b64 s[4:5], vcc
	s_xor_b64 s[4:5], exec, s[4:5]
	s_cbranch_execz .LBB0_249
	s_add_i32 s6, s22, 0x900
	s_mov_b32 s7, 0
	s_lshl_b64 s[6:7], s[6:7], 2
	s_add_u32 s8, s2, s6
	s_addc_u32 s9, s3, s7
	s_waitcnt lgkmcnt(0)
	v_mov_b32_e32 v0, 0
	global_load_dword v2, v0, s[8:9] sc1
	s_waitcnt vmcnt(0)
	v_cmp_eq_u32_e32 vcc, v2, v1
	s_and_saveexec_b64 s[6:7], vcc
	s_cbranch_execz .LBB0_248
	s_mov_b32 s20, 1
	s_mov_b64 s[10:11], 0
	s_branch .LBB0_239

.LBB0_248:
	s_or_b64 exec, exec, s[6:7]
	s_waitcnt vmcnt(0)
	s_nop 0
	s_waitcnt vmcnt(0)

.LBB0_266:
	s_or_b64 exec, exec, s[4:5]
	s_mov_b64 s[4:5], exec
	v_mbcnt_lo_u32_b32 v0, s4, 0
	v_mbcnt_hi_u32_b32 v0, s5, v0
	s_mov_b32 s9, 0
	v_cmp_eq_u32_e32 vcc, 0, v0
	s_waitcnt vmcnt(0)
	s_nop 0
	s_and_saveexec_b64 s[6:7], vcc
	s_cbranch_execz .LBB0_268
	s_add_i32 s8, s22, 0x900
	s_lshl_b64 s[8:9], s[8:9], 2
	s_add_u32 s2, s2, s8
	s_addc_u32 s3, s3, s9
	s_bcnt1_i32_b64 s4, s[4:5]
	v_mov_b32_e32 v0, 0
	v_mov_b32_e32 v1, s4
	global_atomic_add v0, v1, s[2:3]

.LBB0_420:
	s_or_b64 exec, exec, s[6:7]
	v_cvt_f32_u32_e32 v4, v2
	s_waitcnt vmcnt(0)
	buffer_inv sc1
	v_readfirstlane_b32 s4, v3
	v_sub_u32_e32 v3, 0, v2
	v_rcp_iflag_f32_e32 v4, v4
	v_add_u32_e32 v5, s4, v1
	v_mul_f32_e32 v4, 0x4f7ffffe, v4
	v_cvt_u32_f32_e32 v4, v4
	v_mul_lo_u32 v1, v3, v4
	v_mul_hi_u32 v1, v4, v1
	v_add_u32_e32 v1, v4, v1
	v_mul_hi_u32 v1, v5, v1
	v_mul_lo_u32 v3, v1, v2
	v_sub_u32_e32 v3, v5, v3
	v_add_u32_e32 v4, 1, v1
	v_sub_u32_e32 v6, v3, v2
	v_cmp_ge_u32_e32 vcc, v3, v2
	s_nop 1
	v_cndmask_b32_e32 v1, v1, v4, vcc
	v_cndmask_b32_e32 v3, v3, v6, vcc
	v_add_u32_e32 v4, 1, v1
	v_cmp_ge_u32_e32 vcc, v3, v2
	v_add_u32_e32 v3, 1, v5
	s_nop 0
	v_cndmask_b32_e32 v1, v1, v4, vcc
	v_mul_lo_u32 v4, v2, v1
	v_add_u32_e32 v2, v4, v2
	v_cmp_ne_u32_e32 vcc, v3, v2
	s_and_saveexec_b64 s[4:5], vcc
	s_xor_b64 s[4:5], exec, s[4:5]
	s_cbranch_execz .LBB0_434
	s_add_i32 s66, s22, 0x900
	s_lshl_b64 s[6:7], s[66:67], 2
	s_add_u32 s8, s2, s6
	s_addc_u32 s9, s3, s7
	s_waitcnt lgkmcnt(0)
	global_load_dword v0, v65, s[8:9] sc1
	s_waitcnt vmcnt(0)
	v_cmp_eq_u32_e32 vcc, v0, v1
	s_and_saveexec_b64 s[6:7], vcc
	s_cbranch_execz .LBB0_433
	s_mov_b32 s20, 1
	s_mov_b64 s[10:11], 0
	s_branch .LBB0_424

.LBB0_433:
	s_or_b64 exec, exec, s[6:7]
	s_waitcnt vmcnt(0)
	s_nop 0
	s_waitcnt vmcnt(0)
	s_movk_i32 s57, 0x87
	s_mov_b32 s63, 0x2080000
	s_movk_i32 s66, 0xfff

.LBB0_451:
	s_or_b64 exec, exec, s[4:5]
	s_mov_b64 s[4:5], exec
	v_mbcnt_lo_u32_b32 v0, s4, 0
	v_mbcnt_hi_u32_b32 v0, s5, v0
	v_cmp_eq_u32_e32 vcc, 0, v0
	s_waitcnt vmcnt(0)
	s_nop 0
	s_and_saveexec_b64 s[6:7], vcc
	s_cbranch_execz .LBB0_453
	s_add_i32 s66, s22, 0x900
	s_lshl_b64 s[8:9], s[66:67], 2
	s_add_u32 s2, s2, s8
	s_addc_u32 s3, s3, s9
	s_bcnt1_i32_b64 s4, s[4:5]
	v_mov_b32_e32 v0, s4
	global_atomic_add v65, v0, s[2:3]
	s_movk_i32 s66, 0xfff
	s_mov_b32 s63, 0x2080000
	s_movk_i32 s57, 0x87

.LBB0_960:
	s_or_b64 exec, exec, s[6:7]
	v_cvt_f32_u32_e32 v4, v2
	s_waitcnt vmcnt(0)
	buffer_inv sc1
	v_readfirstlane_b32 s4, v3
	v_sub_u32_e32 v3, 0, v2
	v_rcp_iflag_f32_e32 v4, v4
	v_add_u32_e32 v5, s4, v1
	v_mul_f32_e32 v4, 0x4f7ffffe, v4
	v_cvt_u32_f32_e32 v4, v4
	v_mul_lo_u32 v1, v3, v4
	v_mul_hi_u32 v1, v4, v1
	v_add_u32_e32 v1, v4, v1
	v_mul_hi_u32 v1, v5, v1
	v_mul_lo_u32 v3, v1, v2
	v_sub_u32_e32 v3, v5, v3
	v_add_u32_e32 v4, 1, v1
	v_cmp_ge_u32_e32 vcc, v3, v2
	s_nop 1
	v_cndmask_b32_e32 v1, v1, v4, vcc
	v_sub_u32_e32 v4, v3, v2
	v_cndmask_b32_e32 v3, v3, v4, vcc
	v_add_u32_e32 v4, 1, v1
	v_cmp_ge_u32_e32 vcc, v3, v2
	v_add_u32_e32 v3, 1, v5
	s_nop 0
	v_cndmask_b32_e32 v1, v1, v4, vcc
	v_mul_lo_u32 v4, v2, v1
	v_add_u32_e32 v2, v4, v2
	v_cmp_ne_u32_e32 vcc, v3, v2
	s_and_saveexec_b64 s[4:5], vcc
	s_xor_b64 s[4:5], exec, s[4:5]
	s_cbranch_execz .LBB0_974
	s_add_i32 s66, s22, 0x900
	s_lshl_b64 s[6:7], s[66:67], 2
	s_add_u32 s8, s2, s6
	s_addc_u32 s9, s3, s7
	s_waitcnt lgkmcnt(0)
	global_load_dword v0, v65, s[8:9] sc1
	s_waitcnt vmcnt(0)
	v_cmp_eq_u32_e32 vcc, v0, v1
	s_and_saveexec_b64 s[6:7], vcc
	s_cbranch_execz .LBB0_973
	s_mov_b32 s20, 1
	s_mov_b64 s[10:11], 0
	s_branch .LBB0_964

.LBB0_973:
	s_or_b64 exec, exec, s[6:7]
	s_waitcnt vmcnt(0)
	s_nop 0
	s_waitcnt vmcnt(0)
	s_mov_b32 s63, 0x2080000
	s_movk_i32 s66, 0xfff

.LBB0_991:
	s_or_b64 exec, exec, s[4:5]
	s_mov_b64 s[4:5], exec
	v_mbcnt_lo_u32_b32 v0, s4, 0
	v_mbcnt_hi_u32_b32 v0, s5, v0
	v_cmp_eq_u32_e32 vcc, 0, v0
	s_waitcnt vmcnt(0)
	s_nop 0
	s_and_saveexec_b64 s[6:7], vcc
	s_cbranch_execz .LBB0_993
	s_add_i32 s66, s22, 0x900
	s_lshl_b64 s[8:9], s[66:67], 2
	s_add_u32 s2, s2, s8
	s_addc_u32 s3, s3, s9
	s_bcnt1_i32_b64 s4, s[4:5]
	v_mov_b32_e32 v0, s4
	global_atomic_add v65, v0, s[2:3]
	s_movk_i32 s66, 0xfff
	s_mov_b32 s63, 0x2080000

.LBB0_2382:
	s_or_b64 exec, exec, s[10:11]
	v_cvt_f32_u32_e32 v4, v2
	s_waitcnt vmcnt(0)
	buffer_inv sc1
	v_readfirstlane_b32 s8, v3
	v_sub_u32_e32 v3, 0, v2
	v_rcp_iflag_f32_e32 v4, v4
	v_add_u32_e32 v5, s8, v1
	v_mul_f32_e32 v4, 0x4f7ffffe, v4
	v_cvt_u32_f32_e32 v4, v4
	v_mul_lo_u32 v1, v3, v4
	v_mul_hi_u32 v1, v4, v1
	v_add_u32_e32 v1, v4, v1
	v_mul_hi_u32 v1, v5, v1
	v_mul_lo_u32 v3, v1, v2
	v_sub_u32_e32 v3, v5, v3
	v_add_u32_e32 v4, 1, v1
	v_cmp_ge_u32_e32 vcc, v3, v2
	s_nop 1
	v_cndmask_b32_e32 v1, v1, v4, vcc
	v_sub_u32_e32 v4, v3, v2
	v_cndmask_b32_e32 v3, v3, v4, vcc
	v_add_u32_e32 v4, 1, v1
	v_cmp_ge_u32_e32 vcc, v3, v2
	v_add_u32_e32 v3, 1, v5
	s_nop 0
	v_cndmask_b32_e32 v1, v1, v4, vcc
	v_mul_lo_u32 v4, v2, v1
	v_add_u32_e32 v2, v4, v2
	v_cmp_ne_u32_e32 vcc, v3, v2
	s_and_saveexec_b64 s[8:9], vcc
	s_xor_b64 s[8:9], exec, s[8:9]
	s_cbranch_execz .LBB0_2396
	s_add_i32 s66, s26, 0x900
	s_lshl_b64 s[10:11], s[66:67], 2
	s_add_u32 s12, s6, s10
	s_addc_u32 s13, s7, s11
	s_waitcnt lgkmcnt(0)
	global_load_dword v0, v65, s[12:13] sc1
	s_waitcnt vmcnt(0)
	v_cmp_eq_u32_e32 vcc, v0, v1
	s_and_saveexec_b64 s[10:11], vcc
	s_cbranch_execz .LBB0_2395
	s_mov_b32 s24, 1
	s_mov_b64 s[14:15], 0
	s_branch .LBB0_2386

.LBB0_2395:
	s_or_b64 exec, exec, s[10:11]
	s_waitcnt vmcnt(0)
	s_nop 0
	s_waitcnt vmcnt(0)

.LBB0_2413:
	s_or_b64 exec, exec, s[8:9]
	s_mov_b64 s[8:9], exec
	v_mbcnt_lo_u32_b32 v0, s8, 0
	v_mbcnt_hi_u32_b32 v0, s9, v0
	v_cmp_eq_u32_e32 vcc, 0, v0
	s_waitcnt vmcnt(0)
	s_nop 0
	s_and_saveexec_b64 s[10:11], vcc
	s_cbranch_execz .LBB0_2415
	s_add_i32 s66, s26, 0x900
	s_lshl_b64 s[12:13], s[66:67], 2
	s_add_u32 s6, s6, s12
	s_addc_u32 s7, s7, s13
	s_bcnt1_i32_b64 s8, s[8:9]
	v_mov_b32_e32 v0, s8
	global_atomic_add v65, v0, s[6:7]

.LBB0_2463:
	s_or_b64 exec, exec, s[10:11]
	s_waitcnt vmcnt(0)
	s_nop 0
	s_waitcnt vmcnt(0)
	s_movk_i32 s57, 0x87
	s_mov_b32 s63, 0x2080000
	s_movk_i32 s66, 0xfff

.LBB0_2481:
	s_or_b64 exec, exec, s[8:9]
	s_mov_b64 s[8:9], exec
	v_mbcnt_lo_u32_b32 v0, s8, 0
	v_mbcnt_hi_u32_b32 v0, s9, v0
	v_cmp_eq_u32_e32 vcc, 0, v0
	s_waitcnt vmcnt(0)
	s_nop 0
	s_and_saveexec_b64 s[10:11], vcc
	s_cbranch_execz .LBB0_2483
	s_add_i32 s66, s26, 0x900
	s_lshl_b64 s[12:13], s[66:67], 2
	s_add_u32 s6, s6, s12
	s_addc_u32 s7, s7, s13
	s_bcnt1_i32_b64 s8, s[8:9]
	v_mov_b32_e32 v0, s8
	global_atomic_add v65, v0, s[6:7]
	s_movk_i32 s66, 0xfff
	s_mov_b32 s63, 0x2080000
	s_movk_i32 s57, 0x87

.LBB0_2576:
	s_or_b64 exec, exec, s[4:5]
	s_mov_b64 s[4:5], exec
	v_mbcnt_lo_u32_b32 v0, s4, 0
	v_mbcnt_hi_u32_b32 v0, s5, v0
	v_cmp_eq_u32_e32 vcc, 0, v0
	s_waitcnt vmcnt(0)
	s_nop 0
	s_and_saveexec_b64 s[6:7], vcc
	s_cbranch_execnz .LBB0_2577
	s_getpc_b64 s[98:99]
